# v28 + stick-breaking loop: 8 per-wave done flags read with 4 ds_read_b64 and one wait instead of 6 serialized LDS round trips per iteration
# speedup vs baseline: 1.0183x; 1.0058x over previous
; DI void sb_unit(const bf16* PR, bf16* MIX, char* sm, int b, int h, int qb) {
;     ...
;         __syncthreads();
;         unsigned alld = 1u;
; #pragma unroll
;         for (int w = 0; w < 8; ++w) alld &= misc[2 + (it & 1) * 8 + w];
;         if (alld) break;
.LBB0_334:
	s_lshl_b32 s14, s26, 5
	s_add_i32 s14, s14, 0
	s_add_i32 s14, s14, 0x13500
	v_mov_b32_e32 v0, s14
	s_waitcnt lgkmcnt(0)
	s_barrier
	ds_read_b64 v[246:247], v0 offset:8
	ds_read_b64 v[248:249], v0 offset:16
	ds_read_b64 v[250:251], v0 offset:24
	ds_read_b64 v[254:255], v0 offset:32
	s_sub_i32 s22, s22, 64
	v_add_u32_e32 v218, 64, v218
	s_waitcnt lgkmcnt(0)
	v_and_b32_e32 v2, v246, v247
	v_and_b32_e32 v3, v248, v249
	v_and_b32_e32 v2, v2, v3
	v_and_b32_e32 v3, v250, v251
	v_and_b32_e32 v2, v2, v3
	v_and_b32_e32 v3, v254, v255
	v_and_b32_e32 v0, v2, v3
	v_and_b32_e32 v0, 1, v0
	v_cmp_eq_u32_e64 s[14:15], 1, v0
	s_and_b64 vcc, exec, s[14:15]
	s_cbranch_vccnz .LBB0_375
